# v26 plus a specialised branch-free fused-copy store section for the stride-16 dilated sample units (cpy==1) in the sample attention loop
# baseline (speedup 1.0000x reference)
.LBB0_1284:
	s_waitcnt vmcnt(15)
	v_cvt_pk_bf16_f32 v40, v112, v113
	v_cvt_pk_bf16_f32 v41, v114, v115
	s_waitcnt vmcnt(13)
	v_cvt_pk_bf16_f32 v44, v104, v105
	v_cvt_pk_bf16_f32 v45, v106, v107
	v_cvt_pk_bf16_f32 v42, v116, v117
	v_cvt_pk_bf16_f32 v43, v118, v119
	ds_write2_b64 v174, v[40:41], v[44:45] offset1:72
	s_waitcnt vmcnt(12)
	v_cvt_pk_bf16_f32 v40, v108, v109
	v_cvt_pk_bf16_f32 v41, v110, v111
	v_add_u32_e32 v204, 0x1000, v174
	ds_write2_b64 v204, v[42:43], v[40:41] offset0:64 offset1:136
	s_waitcnt vmcnt(11)
	v_cvt_pk_bf16_f32 v40, v96, v97
	v_cvt_pk_bf16_f32 v41, v98, v99
	s_waitcnt vmcnt(9)
	v_cvt_pk_bf16_f32 v44, v88, v89
	v_cvt_pk_bf16_f32 v45, v90, v91
	v_cvt_pk_bf16_f32 v42, v100, v101
	v_cvt_pk_bf16_f32 v43, v102, v103
	ds_write2_b64 v174, v[40:41], v[44:45] offset0:144 offset1:216
	s_waitcnt vmcnt(8)
	v_cvt_pk_bf16_f32 v40, v92, v93
	v_cvt_pk_bf16_f32 v41, v94, v95
	v_add_u32_e32 v205, 0x1400, v174
	ds_write2_b64 v205, v[42:43], v[40:41] offset0:80 offset1:152
	s_waitcnt vmcnt(7)
	v_cvt_pk_bf16_f32 v40, v80, v81
	v_cvt_pk_bf16_f32 v41, v82, v83
	s_waitcnt vmcnt(5)
	v_cvt_pk_bf16_f32 v44, v64, v65
	v_cvt_pk_bf16_f32 v45, v66, v67
	v_add_u32_e32 v203, 0x800, v174
	v_cvt_pk_bf16_f32 v42, v84, v85
	v_cvt_pk_bf16_f32 v43, v86, v87
	ds_write2_b64 v203, v[40:41], v[44:45] offset0:32 offset1:104
	s_waitcnt vmcnt(4)
	v_cvt_pk_bf16_f32 v40, v68, v69
	v_cvt_pk_bf16_f32 v41, v70, v71
	v_add_u32_e32 v206, 0x1800, v174
	ds_write2_b64 v206, v[42:43], v[40:41] offset0:96 offset1:168
	s_waitcnt vmcnt(3)
	v_cvt_pk_bf16_f32 v40, v72, v73
	v_cvt_pk_bf16_f32 v41, v74, v75
	s_waitcnt vmcnt(1)
	v_cvt_pk_bf16_f32 v44, v32, v33
	v_cvt_pk_bf16_f32 v45, v34, v35
	ds_write2_b64 v203, v[40:41], v[44:45] offset0:176 offset1:248
	v_cndmask_b32_e64 v44, 0, 1, s[10:11]
	v_cvt_pk_bf16_f32 v42, v76, v77
	v_cvt_pk_bf16_f32 v43, v78, v79
	s_waitcnt vmcnt(0)
	v_cvt_pk_bf16_f32 v40, v36, v37
	v_cvt_pk_bf16_f32 v41, v38, v39
	v_add_u32_e32 v207, 0x1c00, v174
	v_cmp_ne_u32_e64 s[12:13], 1, v44
	s_andn2_b64 vcc, exec, s[10:11]
	ds_write2_b64 v207, v[42:43], v[40:41] offset0:112 offset1:184
	s_cbranch_vccnz .LBB0_1326
	s_cmp_eq_u64 s[8:9], 0
	s_cbranch_scc1 .Lcpy1_stores
	v_add_u32_e32 v41, v199, v201
	v_subrev_u32_e32 v40, 60, v182
	v_add_u32_e32 v42, -8, v41
	v_cmp_ge_i32_e32 vcc, s53, v40
	v_cmp_gt_u32_e64 s[16:17], s92, v42
	s_and_b64 s[16:17], vcc, s[16:17]
	s_and_saveexec_b64 s[82:83], s[16:17]
	s_andn2_b64 vcc, exec, s[8:9]
	s_mov_b64 s[16:17], s[80:81]
	s_cbranch_vccnz .LBB0_1288
	v_cmp_lt_u32_e32 vcc, s93, v41
	v_and_b32_e32 v41, 8, v41
	v_cmp_ne_u32_e64 s[16:17], 0, v41
	s_and_b64 s[16:17], vcc, s[16:17]
	s_andn2_b64 vcc, s[80:81], exec
	s_and_b64 s[16:17], s[16:17], exec
	s_or_b64 s[16:17], vcc, s[16:17]

.Lcpy1_stores:
	v_subrev_u32_e32 v40, 60, v182
	v_add_u32_e32 v41, v199, v201
	v_add_u32_e32 v42, -8, v41
	v_cmp_ge_i32_e32 vcc, s53, v40
	v_cmp_gt_u32_e64 s[16:17], s92, v42
	s_and_b64 s[16:17], vcc, s[16:17]
	s_and_saveexec_b64 s[82:83], s[16:17]
	v_add_u32_e32 v120, v156, v200
	v_lshl_add_u64 v[44:45], v[120:121], 2, v[144:145]
	v_lshl_add_u64 v[42:43], v[120:121], 2, v[146:147]
	global_store_dwordx4 v[44:45], v[112:115], off nt
	global_store_dwordx4 v[42:43], v[116:119], off nt
	s_or_b64 exec, exec, s[82:83]
	v_add_u32_e32 v41, v183, v201
	v_add_u32_e32 v42, -8, v41
	v_cmp_ge_i32_e32 vcc, s48, v40
	v_cmp_gt_u32_e64 s[16:17], s92, v42
	s_and_b64 s[16:17], vcc, s[16:17]
	s_and_saveexec_b64 s[82:83], s[16:17]
	v_add_u32_e32 v120, v156, v184
	v_lshl_add_u64 v[44:45], v[120:121], 2, v[144:145]
	v_lshl_add_u64 v[42:43], v[120:121], 2, v[146:147]
	global_store_dwordx4 v[44:45], v[104:107], off nt
	global_store_dwordx4 v[42:43], v[108:111], off nt
	s_or_b64 exec, exec, s[82:83]
	v_add_u32_e32 v41, v187, v201
	v_add_u32_e32 v42, -8, v41
	v_cmp_ge_i32_e32 vcc, s49, v40
	v_cmp_gt_u32_e64 s[16:17], s92, v42
	s_and_b64 s[16:17], vcc, s[16:17]
	s_and_saveexec_b64 s[82:83], s[16:17]
	v_add_u32_e32 v120, v156, v188
	v_lshl_add_u64 v[44:45], v[120:121], 2, v[144:145]
	v_lshl_add_u64 v[42:43], v[120:121], 2, v[146:147]
	global_store_dwordx4 v[44:45], v[96:99], off nt
	global_store_dwordx4 v[42:43], v[100:103], off nt
	s_or_b64 exec, exec, s[82:83]
	v_add_u32_e32 v41, v189, v201
	v_add_u32_e32 v42, -8, v41
	v_cmp_ge_i32_e32 vcc, s56, v40
	v_cmp_gt_u32_e64 s[16:17], s92, v42
	s_and_b64 s[16:17], vcc, s[16:17]
	s_and_saveexec_b64 s[82:83], s[16:17]
	v_add_u32_e32 v120, v156, v190
	v_lshl_add_u64 v[44:45], v[120:121], 2, v[144:145]
	v_lshl_add_u64 v[42:43], v[120:121], 2, v[146:147]
	global_store_dwordx4 v[44:45], v[88:91], off nt
	global_store_dwordx4 v[42:43], v[92:95], off nt
	s_or_b64 exec, exec, s[82:83]
	v_add_u32_e32 v41, v191, v201
	v_add_u32_e32 v42, -8, v41
	v_cmp_ge_i32_e32 vcc, s42, v40
	v_cmp_gt_u32_e64 s[16:17], s92, v42
	s_and_b64 s[16:17], vcc, s[16:17]
	s_and_saveexec_b64 s[82:83], s[16:17]
	v_add_u32_e32 v120, v156, v192
	v_lshl_add_u64 v[44:45], v[120:121], 2, v[144:145]
	v_lshl_add_u64 v[42:43], v[120:121], 2, v[146:147]
	global_store_dwordx4 v[44:45], v[80:83], off nt
	global_store_dwordx4 v[42:43], v[84:87], off nt
	s_or_b64 exec, exec, s[82:83]
	v_add_u32_e32 v41, v193, v201
	v_add_u32_e32 v42, -8, v41
	v_cmp_ge_i32_e32 vcc, s54, v40
	v_cmp_gt_u32_e64 s[16:17], s92, v42
	s_and_b64 s[16:17], vcc, s[16:17]
	s_and_saveexec_b64 s[82:83], s[16:17]
	v_add_u32_e32 v120, v156, v194
	v_lshl_add_u64 v[44:45], v[120:121], 2, v[144:145]
	v_lshl_add_u64 v[42:43], v[120:121], 2, v[146:147]
	global_store_dwordx4 v[44:45], v[64:67], off nt
	global_store_dwordx4 v[42:43], v[68:71], off nt
	s_or_b64 exec, exec, s[82:83]
	v_add_u32_e32 v41, v195, v201
	v_add_u32_e32 v42, -8, v41
	v_cmp_ge_i32_e32 vcc, s50, v40
	v_cmp_gt_u32_e64 s[16:17], s92, v42
	s_and_b64 s[16:17], vcc, s[16:17]
	s_and_saveexec_b64 s[82:83], s[16:17]
	v_add_u32_e32 v120, v156, v196
	v_lshl_add_u64 v[44:45], v[120:121], 2, v[144:145]
	v_lshl_add_u64 v[42:43], v[120:121], 2, v[146:147]
	global_store_dwordx4 v[44:45], v[72:75], off nt
	global_store_dwordx4 v[42:43], v[76:79], off nt
	s_or_b64 exec, exec, s[82:83]
	v_add_u32_e32 v41, v197, v201
	v_add_u32_e32 v42, -8, v41
	v_cmp_ge_i32_e32 vcc, s34, v40
	v_cmp_gt_u32_e64 s[16:17], s92, v42
	s_and_b64 s[16:17], vcc, s[16:17]
	s_and_saveexec_b64 s[82:83], s[16:17]
	v_add_u32_e32 v120, v156, v198
	v_lshl_add_u64 v[44:45], v[120:121], 2, v[144:145]
	v_lshl_add_u64 v[42:43], v[120:121], 2, v[146:147]
	global_store_dwordx4 v[44:45], v[32:35], off nt
	global_store_dwordx4 v[42:43], v[36:39], off nt
	s_or_b64 exec, exec, s[82:83]
	s_branch .LBB0_1326
